# pipelined epilogue also for the split-K partial units of the context rows
# baseline (speedup 1.0000x reference)
;     __device__ __forceinline__ void operator()(const f32x4 (&acc)[2][2][4][2], const Unit& u, int wr, int wc, int fr, int fq) const {
;         const float* gate = MODl + tile_w(u.pm) * NMOD + gate_chunk * 1024;
;         const bool part = u.ko != 0;
;         float* base = part ? PART + ((size_t)((u.ko >> 8) - 1) * 512 + (u.pm == 32 ? 0 : 256) + wr * 64 + fr) * DM : H + (size_t)(u.pm * BM + wr * 64 + fr) * DM;
; #pragma unroll
;         for (int bj = 0; bj < 2; ++bj)
; #pragma unroll
;             for (int n = 0; n < 2; ++n) {
;                 const int col = u.pn * BM + bj * HALF + wc * 32 + n * 16 + fq * 4;
;                 const f32x4 gv = *(const f32x4*)(gate + col) * coef;
;                 f32x4 old[2][4];
; #pragma unroll
;                 for (int ai = 0; ai < 2; ++ai)
; #pragma unroll
;                     for (int m = 0; m < 4; ++m) old[ai][m] = part ? (f32x4){0.f, 0.f, 0.f, 0.f} : *(const f32x4*)(base + (size_t)(ai * HALF + m * 16) * DM + col);
; #pragma unroll
;                 for (int ai = 0; ai < 2; ++ai)
; #pragma unroll
;                     for (int m = 0; m < 4; ++m) *(f32x4*)(base + (size_t)(ai * HALF + m * 16) * DM + col) = old[ai][m] + gv * acc[ai][bj][m][n];
.LBB0_276:
	s_lshr_b32 s8, s53, 31
	s_ashr_i32 s9, s53, 3
	s_add_i32 s8, s9, s8
	s_mul_i32 s9, s8, 0xffffffdf
	s_add_i32 s9, s9, s79
	s_mulk_i32 s8, 0x2400
	s_cmp_lg_u32 s9, 32
	s_cselect_b32 s8, s8, 0x4800
	s_ashr_i32 s9, s8, 31
	s_waitcnt vmcnt(0)
	v_or_b32_e32 v130, s23, v180
	s_lshl_b64 s[8:9], s[8:9], 2
	v_lshl_or_b32 v130, s61, 8, v130
	s_add_u32 s8, s71, s8
	v_ashrrev_i32_e32 v131, 31, v130
	s_addc_u32 s9, s65, s9
	v_lshlrev_b64 v[130:131], 2, v[130:131]
	v_lshl_add_u64 v[210:211], s[8:9], 0, v[130:131]
	v_lshl_add_u64 v[212:213], v[128:129], 0, v[130:131]
	s_and_b64 vcc, exec, s[10:11]
	s_cbranch_vccz .Ler_part
	global_load_dwordx4 v[128:131], v[210:211], off offset:0
	global_load_dwordx4 v[132:135], v[210:211], off offset:64
	global_load_dwordx4 v[136:139], v[210:211], off offset:512
	global_load_dwordx4 v[140:143], v[210:211], off offset:576
	s_mov_b32 s13, 0
	s_mov_b32 s12, 0x10000
	v_lshl_add_u64 v[246:247], v[212:213], 0, s[12:13]
	s_mov_b32 s12, 0x20000
	v_lshl_add_u64 v[248:249], v[212:213], 0, s[12:13]
	s_mov_b32 s12, 0x30000
	v_lshl_add_u64 v[250:251], v[212:213], 0, s[12:13]
	s_mov_b32 s12, 0x80000
	v_lshl_add_u64 v[252:253], v[212:213], 0, s[12:13]
	s_mov_b32 s12, 0x90000
	v_lshl_add_u64 v[218:219], v[212:213], 0, s[12:13]
	s_mov_b32 s12, 0xa0000
	v_lshl_add_u64 v[220:221], v[212:213], 0, s[12:13]
	s_mov_b32 s12, 0xb0000
	v_lshl_add_u64 v[214:215], v[212:213], 0, s[12:13]
	global_load_dwordx4 v[144:147], v[212:213], off offset:0
	global_load_dwordx4 v[148:151], v[212:213], off offset:64
	global_load_dwordx4 v[152:155], v[212:213], off offset:512
	global_load_dwordx4 v[156:159], v[212:213], off offset:576
	global_load_dwordx4 v[160:163], v[246:247], off offset:0
	global_load_dwordx4 v[234:237], v[246:247], off offset:64
	global_load_dwordx4 v[238:241], v[246:247], off offset:512
	global_load_dwordx4 v[242:245], v[246:247], off offset:576
	v_mov_b32_e32 v171, v170
	s_waitcnt vmcnt(8)
	v_pk_mul_f32 v[130:131], v[170:171], v[130:131]
	v_pk_mul_f32 v[128:129], v[172:173], v[128:129]
	v_pk_mul_f32 v[134:135], v[170:171], v[134:135]
	v_pk_mul_f32 v[132:133], v[172:173], v[132:133]
	v_pk_mul_f32 v[138:139], v[170:171], v[138:139]
	v_pk_mul_f32 v[136:137], v[172:173], v[136:137]
	v_pk_mul_f32 v[142:143], v[170:171], v[142:143]
	v_pk_mul_f32 v[140:141], v[172:173], v[140:141]
	s_waitcnt vmcnt(7)
	v_pk_fma_f32 v[146:147], v[126:127], v[130:131], v[146:147]
	v_pk_fma_f32 v[144:145], v[124:125], v[128:129], v[144:145]
	global_store_dwordx4 v[212:213], v[144:147], off offset:0
	s_nop 0
	global_load_dwordx4 v[144:147], v[248:249], off offset:0
	s_waitcnt vmcnt(8)
	v_pk_fma_f32 v[150:151], v[118:119], v[134:135], v[150:151]
	v_pk_fma_f32 v[148:149], v[116:117], v[132:133], v[148:149]
	global_store_dwordx4 v[212:213], v[148:151], off offset:64
	s_nop 0
	global_load_dwordx4 v[148:151], v[248:249], off offset:64
	s_waitcnt vmcnt(9)
	v_pk_fma_f32 v[154:155], v[122:123], v[138:139], v[154:155]
	v_pk_fma_f32 v[152:153], v[120:121], v[136:137], v[152:153]
	global_store_dwordx4 v[212:213], v[152:155], off offset:512
	s_nop 0
	global_load_dwordx4 v[152:155], v[248:249], off offset:512
	s_waitcnt vmcnt(10)
	v_pk_fma_f32 v[158:159], v[114:115], v[142:143], v[158:159]
	v_pk_fma_f32 v[156:157], v[112:113], v[140:141], v[156:157]
	global_store_dwordx4 v[212:213], v[156:159], off offset:576
	s_nop 0
	global_load_dwordx4 v[156:159], v[248:249], off offset:576
	s_waitcnt vmcnt(11)
	v_pk_fma_f32 v[162:163], v[110:111], v[130:131], v[162:163]
	v_pk_fma_f32 v[160:161], v[108:109], v[128:129], v[160:161]
	global_store_dwordx4 v[246:247], v[160:163], off offset:0
	s_nop 0
	global_load_dwordx4 v[160:163], v[250:251], off offset:0
	s_waitcnt vmcnt(12)
	v_pk_fma_f32 v[236:237], v[102:103], v[134:135], v[236:237]
	v_pk_fma_f32 v[234:235], v[100:101], v[132:133], v[234:235]
	global_store_dwordx4 v[246:247], v[234:237], off offset:64
	s_nop 0
	global_load_dwordx4 v[234:237], v[250:251], off offset:64
	s_waitcnt vmcnt(13)
	v_pk_fma_f32 v[240:241], v[106:107], v[138:139], v[240:241]
	v_pk_fma_f32 v[238:239], v[104:105], v[136:137], v[238:239]
	global_store_dwordx4 v[246:247], v[238:241], off offset:512
	s_nop 0
	global_load_dwordx4 v[238:241], v[250:251], off offset:512
	s_waitcnt vmcnt(14)
	v_pk_fma_f32 v[244:245], v[98:99], v[142:143], v[244:245]
	v_pk_fma_f32 v[242:243], v[96:97], v[140:141], v[242:243]
	global_store_dwordx4 v[246:247], v[242:245], off offset:576
	s_nop 0
	global_load_dwordx4 v[242:245], v[250:251], off offset:576
	s_waitcnt vmcnt(14)
	v_pk_fma_f32 v[146:147], v[94:95], v[130:131], v[146:147]
	v_pk_fma_f32 v[144:145], v[92:93], v[128:129], v[144:145]
	global_store_dwordx4 v[248:249], v[144:147], off offset:0
	s_nop 0
	global_load_dwordx4 v[144:147], v[252:253], off offset:0
	s_waitcnt vmcnt(14)
	v_pk_fma_f32 v[150:151], v[86:87], v[134:135], v[150:151]
	v_pk_fma_f32 v[148:149], v[84:85], v[132:133], v[148:149]
	global_store_dwordx4 v[248:249], v[148:151], off offset:64
	s_nop 0
	global_load_dwordx4 v[148:151], v[252:253], off offset:64
	s_waitcnt vmcnt(14)
	v_pk_fma_f32 v[154:155], v[90:91], v[138:139], v[154:155]
	v_pk_fma_f32 v[152:153], v[88:89], v[136:137], v[152:153]
	global_store_dwordx4 v[248:249], v[152:155], off offset:512
	s_nop 0
	global_load_dwordx4 v[152:155], v[252:253], off offset:512
	s_waitcnt vmcnt(14)
	v_pk_fma_f32 v[158:159], v[82:83], v[142:143], v[158:159]
	v_pk_fma_f32 v[156:157], v[80:81], v[140:141], v[156:157]
	global_store_dwordx4 v[248:249], v[156:159], off offset:576
	s_nop 0
	global_load_dwordx4 v[156:159], v[252:253], off offset:576
	s_waitcnt vmcnt(14)
;     __device__ __forceinline__ void operator()(const f32x4 (&acc)[2][2][4][2], const Unit& u, int wr, int wc, int fr, int fq) const {
;     ...
;                     for (int m = 0; m < 4; ++m) old[ai][m] = part ? (f32x4){0.f, 0.f, 0.f, 0.f} : *(const f32x4*)(base + (size_t)(ai * HALF + m * 16) * DM + col);
; #pragma unroll
;                 for (int ai = 0; ai < 2; ++ai)
; #pragma unroll
;                     for (int m = 0; m < 4; ++m) *(f32x4*)(base + (size_t)(ai * HALF + m * 16) * DM + col) = old[ai][m] + gv * acc[ai][bj][m][n];
	v_pk_fma_f32 v[162:163], v[78:79], v[130:131], v[162:163]
	v_pk_fma_f32 v[160:161], v[76:77], v[128:129], v[160:161]
	global_store_dwordx4 v[250:251], v[160:163], off offset:0
	s_nop 0
	global_load_dwordx4 v[160:163], v[218:219], off offset:0
	s_waitcnt vmcnt(14)
	v_pk_fma_f32 v[236:237], v[70:71], v[134:135], v[236:237]
	v_pk_fma_f32 v[234:235], v[68:69], v[132:133], v[234:235]
	global_store_dwordx4 v[250:251], v[234:237], off offset:64
	s_nop 0
	global_load_dwordx4 v[234:237], v[218:219], off offset:64
	s_waitcnt vmcnt(14)
	v_pk_fma_f32 v[240:241], v[74:75], v[138:139], v[240:241]
	v_pk_fma_f32 v[238:239], v[72:73], v[136:137], v[238:239]
	global_store_dwordx4 v[250:251], v[238:241], off offset:512
	s_nop 0
	global_load_dwordx4 v[238:241], v[218:219], off offset:512
	s_waitcnt vmcnt(14)
	v_pk_fma_f32 v[244:245], v[66:67], v[142:143], v[244:245]
	v_pk_fma_f32 v[242:243], v[64:65], v[140:141], v[242:243]
	global_store_dwordx4 v[250:251], v[242:245], off offset:576
	s_nop 0
	global_load_dwordx4 v[242:245], v[218:219], off offset:576
	s_waitcnt vmcnt(14)
	v_pk_fma_f32 v[146:147], v[62:63], v[130:131], v[146:147]
	v_pk_fma_f32 v[144:145], v[60:61], v[128:129], v[144:145]
	global_store_dwordx4 v[252:253], v[144:147], off offset:0
	s_nop 0
	global_load_dwordx4 v[144:147], v[220:221], off offset:0
	s_waitcnt vmcnt(14)
	v_pk_fma_f32 v[150:151], v[54:55], v[134:135], v[150:151]
	v_pk_fma_f32 v[148:149], v[52:53], v[132:133], v[148:149]
	global_store_dwordx4 v[252:253], v[148:151], off offset:64
	s_nop 0
	global_load_dwordx4 v[148:151], v[220:221], off offset:64
	s_waitcnt vmcnt(14)
	v_pk_fma_f32 v[154:155], v[58:59], v[138:139], v[154:155]
	v_pk_fma_f32 v[152:153], v[56:57], v[136:137], v[152:153]
	global_store_dwordx4 v[252:253], v[152:155], off offset:512
	s_nop 0
	global_load_dwordx4 v[152:155], v[220:221], off offset:512
	s_waitcnt vmcnt(14)
	v_pk_fma_f32 v[158:159], v[50:51], v[142:143], v[158:159]
	v_pk_fma_f32 v[156:157], v[48:49], v[140:141], v[156:157]
	global_store_dwordx4 v[252:253], v[156:159], off offset:576
	s_nop 0
	global_load_dwordx4 v[156:159], v[220:221], off offset:576
	s_waitcnt vmcnt(14)
	v_pk_fma_f32 v[162:163], v[46:47], v[130:131], v[162:163]
	v_pk_fma_f32 v[160:161], v[44:45], v[128:129], v[160:161]
	global_store_dwordx4 v[218:219], v[160:163], off offset:0
	s_nop 0
	global_load_dwordx4 v[160:163], v[214:215], off offset:0
	s_waitcnt vmcnt(14)
	v_pk_fma_f32 v[236:237], v[38:39], v[134:135], v[236:237]
	v_pk_fma_f32 v[234:235], v[36:37], v[132:133], v[234:235]
	global_store_dwordx4 v[218:219], v[234:237], off offset:64
	s_nop 0
	global_load_dwordx4 v[234:237], v[214:215], off offset:64
	s_waitcnt vmcnt(14)
	v_pk_fma_f32 v[240:241], v[42:43], v[138:139], v[240:241]
	v_pk_fma_f32 v[238:239], v[40:41], v[136:137], v[238:239]
	global_store_dwordx4 v[218:219], v[238:241], off offset:512
	s_nop 0
	global_load_dwordx4 v[238:241], v[214:215], off offset:512
	s_waitcnt vmcnt(14)
	v_pk_fma_f32 v[244:245], v[34:35], v[142:143], v[244:245]
	v_pk_fma_f32 v[242:243], v[32:33], v[140:141], v[242:243]
	global_store_dwordx4 v[218:219], v[242:245], off offset:576
	s_nop 0
	global_load_dwordx4 v[242:245], v[214:215], off offset:576
	s_waitcnt vmcnt(14)
	v_pk_fma_f32 v[146:147], v[30:31], v[130:131], v[146:147]
	v_pk_fma_f32 v[144:145], v[28:29], v[128:129], v[144:145]
	global_store_dwordx4 v[220:221], v[144:147], off offset:0
	s_waitcnt vmcnt(13)
	v_pk_fma_f32 v[150:151], v[22:23], v[134:135], v[150:151]
	v_pk_fma_f32 v[148:149], v[20:21], v[132:133], v[148:149]
	global_store_dwordx4 v[220:221], v[148:151], off offset:64
	s_waitcnt vmcnt(12)
	v_pk_fma_f32 v[154:155], v[26:27], v[138:139], v[154:155]
	v_pk_fma_f32 v[152:153], v[24:25], v[136:137], v[152:153]
	global_store_dwordx4 v[220:221], v[152:155], off offset:512
	s_waitcnt vmcnt(11)
	v_pk_fma_f32 v[158:159], v[18:19], v[142:143], v[158:159]
	v_pk_fma_f32 v[156:157], v[16:17], v[140:141], v[156:157]
	global_store_dwordx4 v[220:221], v[156:159], off offset:576
	s_waitcnt vmcnt(10)
	v_pk_fma_f32 v[162:163], v[14:15], v[130:131], v[162:163]
	v_pk_fma_f32 v[160:161], v[12:13], v[128:129], v[160:161]
	global_store_dwordx4 v[214:215], v[160:163], off offset:0
	s_waitcnt vmcnt(9)
	v_pk_fma_f32 v[236:237], v[6:7], v[134:135], v[236:237]
	v_pk_fma_f32 v[234:235], v[4:5], v[132:133], v[234:235]
	global_store_dwordx4 v[214:215], v[234:237], off offset:64
	s_waitcnt vmcnt(8)
	v_pk_fma_f32 v[240:241], v[10:11], v[138:139], v[240:241]
	v_pk_fma_f32 v[238:239], v[8:9], v[136:137], v[238:239]
	global_store_dwordx4 v[214:215], v[238:241], off offset:512
	s_waitcnt vmcnt(7)
	v_pk_fma_f32 v[244:245], v[2:3], v[142:143], v[244:245]
	v_pk_fma_f32 v[242:243], v[0:1], v[140:141], v[242:243]
	global_store_dwordx4 v[214:215], v[242:245], off offset:576
	s_branch .LBB0_341
;     __device__ __forceinline__ void operator()(const f32x4 (&acc)[2][2][4][2], const Unit& u, int wr, int wc, int fr, int fq) const {
;         const float* gate = MODl + tile_w(u.pm) * NMOD + gate_chunk * 1024;
;         const bool part = u.ko != 0;
;         float* base = part ? PART + ((size_t)((u.ko >> 8) - 1) * 512 + (u.pm == 32 ? 0 : 256) + wr * 64 + fr) * DM : H + (size_t)(u.pm * BM + wr * 64 + fr) * DM;
; #pragma unroll
;         for (int bj = 0; bj < 2; ++bj)
; #pragma unroll
;             for (int n = 0; n < 2; ++n) {
;                 const int col = u.pn * BM + bj * HALF + wc * 32 + n * 16 + fq * 4;
;                 const f32x4 gv = *(const f32x4*)(gate + col) * coef;
;                 f32x4 old[2][4];
; #pragma unroll
;                 for (int ai = 0; ai < 2; ++ai)
; #pragma unroll
;                     for (int m = 0; m < 4; ++m) old[ai][m] = part ? (f32x4){0.f, 0.f, 0.f, 0.f} : *(const f32x4*)(base + (size_t)(ai * HALF + m * 16) * DM + col);
; #pragma unroll
;                 for (int ai = 0; ai < 2; ++ai)
; #pragma unroll
;                     for (int m = 0; m < 4; ++m) *(f32x4*)(base + (size_t)(ai * HALF + m * 16) * DM + col) = old[ai][m] + gv * acc[ai][bj][m][n];
.Ler_part:
	global_load_dwordx4 v[128:131], v[210:211], off offset:0
	global_load_dwordx4 v[132:135], v[210:211], off offset:64
	global_load_dwordx4 v[136:139], v[210:211], off offset:512
	global_load_dwordx4 v[140:143], v[210:211], off offset:576
	s_mov_b32 s13, 0
	s_mov_b32 s12, 0x10000
	v_lshl_add_u64 v[246:247], v[212:213], 0, s[12:13]
	s_mov_b32 s12, 0x20000
	v_lshl_add_u64 v[248:249], v[212:213], 0, s[12:13]
	s_mov_b32 s12, 0x30000
	v_lshl_add_u64 v[250:251], v[212:213], 0, s[12:13]
	s_mov_b32 s12, 0x80000
	v_lshl_add_u64 v[252:253], v[212:213], 0, s[12:13]
	s_mov_b32 s12, 0x90000
	v_lshl_add_u64 v[218:219], v[212:213], 0, s[12:13]
	s_mov_b32 s12, 0xa0000
	v_lshl_add_u64 v[220:221], v[212:213], 0, s[12:13]
	s_mov_b32 s12, 0xb0000
	v_lshl_add_u64 v[214:215], v[212:213], 0, s[12:13]
	v_mov_b32_e32 v171, v170
	s_waitcnt vmcnt(0)
	v_pk_mul_f32 v[130:131], v[170:171], v[130:131]
	v_pk_mul_f32 v[128:129], v[172:173], v[128:129]
	v_pk_mul_f32 v[134:135], v[170:171], v[134:135]
	v_pk_mul_f32 v[132:133], v[172:173], v[132:133]
	v_pk_mul_f32 v[138:139], v[170:171], v[138:139]
	v_pk_mul_f32 v[136:137], v[172:173], v[136:137]
	v_pk_mul_f32 v[142:143], v[170:171], v[142:143]
	v_pk_mul_f32 v[140:141], v[172:173], v[140:141]
	v_pk_mul_f32 v[146:147], v[126:127], v[130:131]
	v_pk_mul_f32 v[144:145], v[124:125], v[128:129]
	global_store_dwordx4 v[212:213], v[144:147], off offset:0
	v_pk_mul_f32 v[150:151], v[118:119], v[134:135]
	v_pk_mul_f32 v[148:149], v[116:117], v[132:133]
	global_store_dwordx4 v[212:213], v[148:151], off offset:64
	v_pk_mul_f32 v[154:155], v[122:123], v[138:139]
	v_pk_mul_f32 v[152:153], v[120:121], v[136:137]
	global_store_dwordx4 v[212:213], v[152:155], off offset:512
	v_pk_mul_f32 v[158:159], v[114:115], v[142:143]
	v_pk_mul_f32 v[156:157], v[112:113], v[140:141]
	global_store_dwordx4 v[212:213], v[156:159], off offset:576
	v_pk_mul_f32 v[162:163], v[110:111], v[130:131]
	v_pk_mul_f32 v[160:161], v[108:109], v[128:129]
	global_store_dwordx4 v[246:247], v[160:163], off offset:0
	v_pk_mul_f32 v[236:237], v[102:103], v[134:135]
	v_pk_mul_f32 v[234:235], v[100:101], v[132:133]
	global_store_dwordx4 v[246:247], v[234:237], off offset:64
	v_pk_mul_f32 v[240:241], v[106:107], v[138:139]
	v_pk_mul_f32 v[238:239], v[104:105], v[136:137]
	global_store_dwordx4 v[246:247], v[238:241], off offset:512
	v_pk_mul_f32 v[244:245], v[98:99], v[142:143]
	v_pk_mul_f32 v[242:243], v[96:97], v[140:141]
	global_store_dwordx4 v[246:247], v[242:245], off offset:576
	v_pk_mul_f32 v[146:147], v[94:95], v[130:131]
	v_pk_mul_f32 v[144:145], v[92:93], v[128:129]
	global_store_dwordx4 v[248:249], v[144:147], off offset:0
	v_pk_mul_f32 v[150:151], v[86:87], v[134:135]
	v_pk_mul_f32 v[148:149], v[84:85], v[132:133]
	global_store_dwordx4 v[248:249], v[148:151], off offset:64
	v_pk_mul_f32 v[154:155], v[90:91], v[138:139]
	v_pk_mul_f32 v[152:153], v[88:89], v[136:137]
	global_store_dwordx4 v[248:249], v[152:155], off offset:512
	v_pk_mul_f32 v[158:159], v[82:83], v[142:143]
	v_pk_mul_f32 v[156:157], v[80:81], v[140:141]
	global_store_dwordx4 v[248:249], v[156:159], off offset:576
	v_pk_mul_f32 v[162:163], v[78:79], v[130:131]
	v_pk_mul_f32 v[160:161], v[76:77], v[128:129]
	global_store_dwordx4 v[250:251], v[160:163], off offset:0
	v_pk_mul_f32 v[236:237], v[70:71], v[134:135]
	v_pk_mul_f32 v[234:235], v[68:69], v[132:133]
	global_store_dwordx4 v[250:251], v[234:237], off offset:64
	v_pk_mul_f32 v[240:241], v[74:75], v[138:139]
	v_pk_mul_f32 v[238:239], v[72:73], v[136:137]
	global_store_dwordx4 v[250:251], v[238:241], off offset:512
	v_pk_mul_f32 v[244:245], v[66:67], v[142:143]
	v_pk_mul_f32 v[242:243], v[64:65], v[140:141]
	global_store_dwordx4 v[250:251], v[242:245], off offset:576
	v_pk_mul_f32 v[146:147], v[62:63], v[130:131]
	v_pk_mul_f32 v[144:145], v[60:61], v[128:129]
	global_store_dwordx4 v[252:253], v[144:147], off offset:0
	v_pk_mul_f32 v[150:151], v[54:55], v[134:135]
	v_pk_mul_f32 v[148:149], v[52:53], v[132:133]
	global_store_dwordx4 v[252:253], v[148:151], off offset:64
	v_pk_mul_f32 v[154:155], v[58:59], v[138:139]
	v_pk_mul_f32 v[152:153], v[56:57], v[136:137]
	global_store_dwordx4 v[252:253], v[152:155], off offset:512
	v_pk_mul_f32 v[158:159], v[50:51], v[142:143]
	v_pk_mul_f32 v[156:157], v[48:49], v[140:141]
	global_store_dwordx4 v[252:253], v[156:159], off offset:576
	v_pk_mul_f32 v[162:163], v[46:47], v[130:131]
	v_pk_mul_f32 v[160:161], v[44:45], v[128:129]
	global_store_dwordx4 v[218:219], v[160:163], off offset:0
	v_pk_mul_f32 v[236:237], v[38:39], v[134:135]
	v_pk_mul_f32 v[234:235], v[36:37], v[132:133]
	global_store_dwordx4 v[218:219], v[234:237], off offset:64
	v_pk_mul_f32 v[240:241], v[42:43], v[138:139]
	v_pk_mul_f32 v[238:239], v[40:41], v[136:137]
	global_store_dwordx4 v[218:219], v[238:241], off offset:512
	v_pk_mul_f32 v[244:245], v[34:35], v[142:143]
	v_pk_mul_f32 v[242:243], v[32:33], v[140:141]
	global_store_dwordx4 v[218:219], v[242:245], off offset:576
	v_pk_mul_f32 v[146:147], v[30:31], v[130:131]
	v_pk_mul_f32 v[144:145], v[28:29], v[128:129]
	global_store_dwordx4 v[220:221], v[144:147], off offset:0
	v_pk_mul_f32 v[150:151], v[22:23], v[134:135]
	v_pk_mul_f32 v[148:149], v[20:21], v[132:133]
	global_store_dwordx4 v[220:221], v[148:151], off offset:64
	v_pk_mul_f32 v[154:155], v[26:27], v[138:139]
	v_pk_mul_f32 v[152:153], v[24:25], v[136:137]
	global_store_dwordx4 v[220:221], v[152:155], off offset:512
	v_pk_mul_f32 v[158:159], v[18:19], v[142:143]
	v_pk_mul_f32 v[156:157], v[16:17], v[140:141]
	global_store_dwordx4 v[220:221], v[156:159], off offset:576
	v_pk_mul_f32 v[162:163], v[14:15], v[130:131]
	v_pk_mul_f32 v[160:161], v[12:13], v[128:129]
	global_store_dwordx4 v[214:215], v[160:163], off offset:0
	v_pk_mul_f32 v[236:237], v[6:7], v[134:135]
	v_pk_mul_f32 v[234:235], v[4:5], v[132:133]
	global_store_dwordx4 v[214:215], v[234:237], off offset:64
	v_pk_mul_f32 v[240:241], v[10:11], v[138:139]
	v_pk_mul_f32 v[238:239], v[8:9], v[136:137]
	global_store_dwordx4 v[214:215], v[238:241], off offset:512
	v_pk_mul_f32 v[244:245], v[2:3], v[142:143]
	v_pk_mul_f32 v[242:243], v[0:1], v[140:141]
	global_store_dwordx4 v[214:215], v[242:245], off offset:576
	s_branch .LBB0_341
	global_load_dwordx4 v[132:135], v[210:211], off
	v_lshl_add_u64 v[212:213], v[128:129], 0, v[130:131]
	v_cndmask_b32_e64 v129, 0, 1, s[10:11]
	v_mov_b32_e32 v128, 0
	v_cmp_ne_u32_e64 s[8:9], 1, v129
	s_andn2_b64 vcc, exec, s[10:11]
	v_mov_b32_e32 v136, 0
	v_mov_b32_e32 v137, 0
	v_mov_b32_e32 v138, 0
	v_mov_b32_e32 v139, 0
	s_mov_b32 s12, 0x30000
	s_mov_b32 s13, 0xa0000
	s_cbranch_vccnz .LBB0_278
	global_load_dwordx4 v[136:139], v[212:213], off
